# v082 + per-unit tile decode of the three large GEMMs: generic division by the (always 8) group size replaced by shift/mask (removes a VALU reciprocal + readfirstlane chain between units)
# baseline (speedup 1.0000x reference)
;     __device__ bool next(int i, Unit& u) const { if (!b.next(i / 3, u)) return false; u.pz = i % 3; return true; }
;     __device__ bool next(int i, Unit& u) const {
;         const long L = (long)i * G + c; if (L >= nwg) return false;
;         int wgid = (int)L; { const int q = nwg / NXCD, r = nwg % NXCD, xcd = wgid % NXCD, off = wgid / NXCD; wgid = (xcd < r ? xcd * (q + 1) : r * (q + 1) + (xcd - r) * q) + off; }
;         const int nig = WGM * nN, gid = wgid / nig, fm = gid * WGM, gsz = (nM - fm) < WGM ? (nM - fm) : WGM;
;         u.pm = fm + ((wgid % nig) % gsz); u.pn = (wgid % nig) / gsz; u.pz = 0; return true;
;     }
.LBB0_366:
	s_add_i32 s45, s45, 1
	s_mul_i32 s2, s45, s13
	s_mul_hi_u32 s3, s45, s14
	s_add_i32 s3, s3, s2
	s_mul_i32 s2, s45, s14
	s_add_u32 s56, s2, s28
	s_addc_u32 s57, s3, s72
	v_cmp_gt_i64_e32 vcc, s[56:57], v[202:203]
	v_cmp_lt_i64_e64 s[2:3], s[56:57], v[250:251]
	s_cbranch_vccnz .LBB0_368
	s_ashr_i32 s8, s56, 31
	s_lshr_b32 s8, s8, 29
	s_add_i32 s8, s56, s8
	s_ashr_i32 s9, s8, 3
	s_and_b32 s8, s8, -8
	s_sub_i32 s8, s56, s8
	s_cmp_lt_i32 s8, 0
	s_movk_i32 s10, 0x161
	s_cselect_b32 s10, s10, 0x160
	s_mul_i32 s8, s8, s10
	s_add_i32 s8, s8, s9
	s_mul_hi_i32 s9, s8, 0x2e8ba2e9
	s_lshr_b32 s10, s9, 31
	s_ashr_i32 s9, s9, 5
	s_add_i32 s9, s9, s10
	s_lshl_b32 s10, s9, 3
	s_sub_i32 s11, 0x80, s10
	s_mulk_i32 s9, 0xb0
	s_sub_i32 s9, s8, s9
	s_lshr_b32 s8, s9, 3
	s_and_b32 s9, s9, 7
	s_add_i32 s10, s10, s9

;     __device__ bool next(int i, Unit& u) const { if (!b.next(i / 3, u)) return false; u.pz = i % 3; return true; }
;     __device__ bool next(int i, Unit& u) const {
;         const long L = (long)i * G + c; if (L >= nwg) return false;
;         int wgid = (int)L; { const int q = nwg / NXCD, r = nwg % NXCD, xcd = wgid % NXCD, off = wgid / NXCD; wgid = (xcd < r ? xcd * (q + 1) : r * (q + 1) + (xcd - r) * q) + off; }
;         const int nig = WGM * nN, gid = wgid / nig, fm = gid * WGM, gsz = (nM - fm) < WGM ? (nM - fm) : WGM;
;         u.pm = fm + ((wgid % nig) % gsz); u.pn = (wgid % nig) / gsz; u.pz = 0; return true;
;     }
.LBB0_556:
	s_add_i32 s40, s40, 1
	s_mul_i32 s2, s40, s13
	s_mul_hi_u32 s3, s40, s14
	s_add_i32 s3, s3, s2
	s_mul_i32 s2, s40, s14
	s_add_u32 s16, s2, s28
	s_addc_u32 s17, s3, s24
	v_mov_b64_e32 v[2:3], 0xa00
	v_cmp_lt_i64_e64 s[2:3], s[16:17], v[2:3]
	v_mov_b64_e32 v[2:3], 0x9ff
	v_cmp_gt_i64_e32 vcc, s[16:17], v[2:3]
	s_cbranch_vccnz .LBB0_558
	s_ashr_i32 s6, s16, 31
	s_lshr_b32 s6, s6, 29
	s_add_i32 s6, s16, s6
	s_ashr_i32 s7, s6, 3
	s_and_b32 s6, s6, -8
	s_sub_i32 s6, s16, s6
	s_cmp_lt_i32 s6, 0
	s_movk_i32 s8, 0x141
	s_cselect_b32 s8, s8, 0x140
	s_mul_i32 s6, s6, s8
	s_add_i32 s6, s6, s7
	s_mul_hi_i32 s7, s6, 0x66666667
	s_lshr_b32 s8, s7, 31
	s_ashr_i32 s7, s7, 6
	s_add_i32 s7, s7, s8
	s_lshl_b32 s8, s7, 3
	s_sub_i32 s9, 0x80, s8
	s_mulk_i32 s7, 0xa0
	s_sub_i32 s7, s6, s7
	s_lshr_b32 s6, s7, 3
	s_and_b32 s7, s7, 7
	s_add_i32 s8, s8, s7

;     __device__ bool next(int i, Unit& u) const { if (!b.next(i / 3, u)) return false; u.pz = i % 3; return true; }
;     __device__ bool next(int i, Unit& u) const {
;         const long L = (long)i * G + c; if (L >= nwg) return false;
;         int wgid = (int)L; { const int q = nwg / NXCD, r = nwg % NXCD, xcd = wgid % NXCD, off = wgid / NXCD; wgid = (xcd < r ? xcd * (q + 1) : r * (q + 1) + (xcd - r) * q) + off; }
;         const int nig = WGM * nN, gid = wgid / nig, fm = gid * WGM, gsz = (nM - fm) < WGM ? (nM - fm) : WGM;
;         u.pm = fm + ((wgid % nig) % gsz); u.pn = (wgid % nig) / gsz; u.pz = 0; return true;
;     }
.LBB0_644:
	s_add_i32 s35, s35, 1
	s_mul_i32 s2, s35, s13
	s_mul_hi_u32 s3, s35, s14
	s_add_i32 s3, s3, s2
	s_mul_i32 s2, s35, s14
	s_add_u32 s10, s2, s28
	s_addc_u32 s11, s3, s15
	v_cmp_gt_i64_e32 vcc, s[10:11], v[202:203]
	v_cmp_lt_i64_e64 s[2:3], s[10:11], v[250:251]
	s_cbranch_vccnz .LBB0_646
	s_ashr_i32 s6, s10, 31
	s_lshr_b32 s6, s6, 29
	s_add_i32 s6, s10, s6
	s_ashr_i32 s7, s6, 3
	s_and_b32 s6, s6, -8
	s_sub_i32 s6, s10, s6
	s_cmp_lt_i32 s6, 0
	s_movk_i32 s8, 0x161
	s_cselect_b32 s8, s8, 0x160
	s_mul_i32 s6, s6, s8
	s_add_i32 s6, s6, s7
	s_mul_hi_i32 s7, s6, 0x2e8ba2e9
	s_lshr_b32 s8, s7, 31
	s_ashr_i32 s7, s7, 5
	s_add_i32 s7, s7, s8
	s_lshl_b32 s8, s7, 3
	s_sub_i32 s9, 0x80, s8
	s_mulk_i32 s7, 0xb0
	s_sub_i32 s7, s6, s7
	s_lshr_b32 s6, s7, 3
	s_and_b32 s7, s7, 7
	s_add_i32 s8, s8, s7
